# v55 + P6 head loop: counted vmcnt waits per q fragment instead of vmcnt(0) after the second MFMA pair; q7 copy moved later
# baseline (speedup 1.0000x reference)
.LBB0_725:
	ds_read_b128 v[0:3], v196
	ds_read_b128 v[124:127], v196 offset:32
	ds_read_b128 v[16:19], v196 offset:8704
	ds_read_b128 v[128:131], v196 offset:8736
	s_and_b32 s2, s33, 3
	s_lshl_b32 s84, s2, 2
	s_waitcnt vmcnt(7) lgkmcnt(3)
	v_mfma_f32_32x32x16_bf16 v[0:15], v[0:3], v[64:67], 0
	s_waitcnt lgkmcnt(1)
	v_mfma_f32_32x32x16_bf16 v[16:31], v[16:19], v[64:67], 0
	s_waitcnt vmcnt(6)
	v_mfma_f32_32x32x16_bf16 v[0:15], v[124:127], v[56:59], v[0:15]
	s_waitcnt lgkmcnt(0)
	v_mfma_f32_32x32x16_bf16 v[16:31], v[128:131], v[56:59], v[16:31]
	ds_read_b128 v[56:59], v196 offset:64
	ds_read_b128 v[64:67], v196 offset:96
	s_waitcnt vmcnt(5)
	s_waitcnt lgkmcnt(1)
	v_mfma_f32_32x32x16_bf16 v[0:15], v[56:59], v[48:51], v[0:15]
	ds_read_b128 v[56:59], v196 offset:8768
	ds_read_b128 v[124:127], v196 offset:8800
	s_waitcnt lgkmcnt(1)
	v_mfma_f32_32x32x16_bf16 v[16:31], v[56:59], v[48:51], v[16:31]
	s_waitcnt vmcnt(4)
	v_mfma_f32_32x32x16_bf16 v[0:15], v[64:67], v[36:39], v[0:15]
	s_waitcnt lgkmcnt(0)
	v_mfma_f32_32x32x16_bf16 v[16:31], v[124:127], v[36:39], v[16:31]
	ds_read_b128 v[36:39], v196 offset:128
	ds_read_b128 v[48:51], v196 offset:160
	s_waitcnt lgkmcnt(1)
	s_waitcnt vmcnt(3)
	v_mfma_f32_32x32x16_bf16 v[0:15], v[36:39], v[68:71], v[0:15]
	ds_read_b128 v[36:39], v196 offset:8832
	ds_read_b128 v[56:59], v196 offset:8864
	s_waitcnt lgkmcnt(1)
	v_mfma_f32_32x32x16_bf16 v[16:31], v[36:39], v[68:71], v[16:31]
	s_waitcnt vmcnt(2)
	v_mfma_f32_32x32x16_bf16 v[0:15], v[48:51], v[60:63], v[0:15]
	ds_read_b128 v[36:39], v196 offset:192
	ds_read_b128 v[48:51], v196 offset:8896
	ds_read_b128 v[124:127], v196 offset:224
	ds_read_b128 v[132:135], v196 offset:8928
	s_waitcnt lgkmcnt(4)
	v_mfma_f32_32x32x16_bf16 v[16:31], v[56:59], v[60:63], v[16:31]
	s_waitcnt lgkmcnt(3)
	s_waitcnt vmcnt(1)
	v_mfma_f32_32x32x16_bf16 v[0:15], v[36:39], v[52:55], v[0:15]
	s_waitcnt vmcnt(0)
	v_mov_b64_e32 v[130:131], v[46:47]
	v_mov_b64_e32 v[128:129], v[44:45]
	v_lshl_add_u64 v[36:37], v[80:81], 0, s[84:85]
	s_lshl_b32 s84, s2, 8
	v_lshl_add_u64 v[44:45], v[78:79], 0, s[84:85]
	s_waitcnt lgkmcnt(2)
	v_mfma_f32_32x32x16_bf16 v[16:31], v[48:51], v[52:55], v[16:31]
	global_load_dword v197, v[36:37], off
	global_load_dwordx4 v[64:67], v[44:45], off
	global_load_dwordx4 v[56:59], v[44:45], off offset:32
	global_load_dwordx4 v[48:51], v[44:45], off offset:64
	s_nop 0
	global_load_dwordx4 v[36:39], v[44:45], off offset:96
	global_load_dwordx4 v[68:71], v[44:45], off offset:128
	global_load_dwordx4 v[60:63], v[44:45], off offset:160
	global_load_dwordx4 v[52:55], v[44:45], off offset:192
	s_nop 0
	global_load_dwordx4 v[44:47], v[44:45], off offset:224
	s_waitcnt lgkmcnt(1)
	v_mfma_f32_32x32x16_bf16 v[0:15], v[124:127], v[128:131], v[0:15]
	v_mov_b32_e32 v126, v110
	v_mov_b32_e32 v127, v111
	s_waitcnt lgkmcnt(0)
	v_mfma_f32_32x32x16_bf16 v[16:31], v[132:135], v[128:131], v[16:31]
	s_andn2_b64 vcc, exec, s[94:95]
	s_mov_b64 s[2:3], -1
	s_cbranch_vccnz .LBB0_727
	v_add_u32_e32 v110, s83, v195
	v_add_u32_e32 v111, s83, v194
	ds_read_b32 v110, v110 offset:8192
	ds_read_b32 v111, v111 offset:8192
	v_add_u32_e32 v124, s83, v192
	v_add_u32_e32 v128, s83, v188
	v_add_u32_e32 v132, s83, v178
	v_add_u32_e32 v199, s83, v162
	ds_read_b32 v124, v124 offset:8192
	ds_read_b32 v128, v128 offset:8192
	ds_read_b32 v132, v132 offset:8192
	ds_read_b32 v199, v199 offset:8192
	s_waitcnt lgkmcnt(4)
	v_add_f32_e32 v111, v16, v111
	v_add_f32_e32 v110, v0, v110
	v_sub_f32_e32 v111, v111, v181
	v_sub_f32_e32 v110, v110, v181
	v_exp_f32_e32 v140, v110
	v_exp_f32_e32 v110, v111
	v_add_u32_e32 v111, s83, v193
	ds_read_b32 v111, v111 offset:8192
	v_add_u32_e32 v125, s83, v190
	v_add_u32_e32 v130, s83, v184
	v_add_u32_e32 v136, s83, v170
	s_waitcnt lgkmcnt(4)
	v_add_f32_e32 v124, v17, v124
	ds_read_b32 v125, v125 offset:8192
	ds_read_b32 v130, v130 offset:8192
	ds_read_b32 v136, v136 offset:8192
	s_waitcnt lgkmcnt(3)
	v_add_f32_e32 v111, v1, v111
	v_sub_f32_e32 v124, v124, v181
	v_sub_f32_e32 v111, v111, v181
	v_exp_f32_e32 v141, v111
	v_exp_f32_e32 v111, v124
	v_add_u32_e32 v124, s83, v191
	ds_read_b32 v124, v124 offset:8192
	v_add_u32_e32 v129, s83, v186
	v_add_u32_e32 v134, s83, v174
	s_waitcnt lgkmcnt(3)
	v_add_f32_e32 v125, v18, v125
	ds_read_b32 v129, v129 offset:8192
	ds_read_b32 v134, v134 offset:8192
	s_waitcnt lgkmcnt(2)
	v_add_f32_e32 v124, v2, v124
	v_sub_f32_e32 v125, v125, v181
	v_sub_f32_e32 v124, v124, v181
	v_exp_f32_e32 v142, v124
	v_exp_f32_e32 v124, v125
	v_add_u32_e32 v125, s83, v189
	ds_read_b32 v125, v125 offset:8192
	v_add_u32_e32 v131, s83, v180
	v_add_u32_e32 v139, s83, v166
	v_add_f32_e32 v128, v19, v128
	ds_read_b32 v131, v131 offset:8192
	ds_read_b32 v139, v139 offset:8192
	s_waitcnt lgkmcnt(2)
	v_add_f32_e32 v125, v3, v125
	v_sub_f32_e32 v128, v128, v181
	v_sub_f32_e32 v125, v125, v181
	v_exp_f32_e32 v143, v125
	v_exp_f32_e32 v125, v128
	v_add_u32_e32 v128, s83, v187
	ds_read_b32 v128, v128 offset:8192
	v_add_u32_e32 v133, s83, v176
	v_add_f32_e32 v129, v20, v129
	ds_read_b32 v133, v133 offset:8192
	v_sub_f32_e32 v129, v129, v181
	s_waitcnt lgkmcnt(1)
	v_add_f32_e32 v128, v4, v128
	v_sub_f32_e32 v128, v128, v181
	v_exp_f32_e32 v144, v128
	v_exp_f32_e32 v128, v129
	v_add_u32_e32 v129, s83, v185
	ds_read_b32 v129, v129 offset:8192
	v_add_u32_e32 v135, s83, v172
	v_add_f32_e32 v130, v21, v130
	ds_read_b32 v135, v135 offset:8192
	v_sub_f32_e32 v130, v130, v181
	s_waitcnt lgkmcnt(1)
	v_add_f32_e32 v129, v5, v129
	v_sub_f32_e32 v129, v129, v181
	v_exp_f32_e32 v145, v129
	v_exp_f32_e32 v129, v130
	v_add_u32_e32 v130, s83, v183
	ds_read_b32 v130, v130 offset:8192
	v_add_u32_e32 v137, s83, v168
	v_add_f32_e32 v131, v22, v131
	ds_read_b32 v137, v137 offset:8192
	v_sub_f32_e32 v131, v131, v181
	s_waitcnt lgkmcnt(1)
	v_add_f32_e32 v130, v6, v130
	v_sub_f32_e32 v130, v130, v181
	v_exp_f32_e32 v146, v130
	v_exp_f32_e32 v130, v131
	v_add_u32_e32 v131, s83, v179
	ds_read_b32 v131, v131 offset:8192
	v_add_u32_e32 v154, s83, v164
	v_add_f32_e32 v132, v23, v132
	ds_read_b32 v154, v154 offset:8192
	v_sub_f32_e32 v132, v132, v181
	s_waitcnt lgkmcnt(1)
	v_add_f32_e32 v131, v7, v131
	v_sub_f32_e32 v131, v131, v181
	v_exp_f32_e32 v147, v131
	v_exp_f32_e32 v131, v132
	v_add_u32_e32 v132, s83, v177
	ds_read_b32 v132, v132 offset:8192
	v_add_f32_e32 v133, v24, v133
	v_sub_f32_e32 v133, v133, v181
	v_add_f32_e32 v134, v25, v134
	v_sub_f32_e32 v134, v134, v181
	s_waitcnt lgkmcnt(0)
	v_add_f32_e32 v132, v8, v132
	v_sub_f32_e32 v132, v132, v181
	v_exp_f32_e32 v148, v132
	v_exp_f32_e32 v132, v133
	v_add_u32_e32 v133, s83, v175
	ds_read_b32 v133, v133 offset:8192
	v_add_f32_e32 v135, v26, v135
	v_sub_f32_e32 v135, v135, v181
	v_add_f32_e32 v136, v27, v136
	v_sub_f32_e32 v136, v136, v181
	s_waitcnt lgkmcnt(0)
	v_add_f32_e32 v133, v9, v133
	v_sub_f32_e32 v133, v133, v181
	v_exp_f32_e32 v149, v133
	v_exp_f32_e32 v133, v134
	v_add_u32_e32 v134, s83, v173
	ds_read_b32 v134, v134 offset:8192
	v_add_f32_e32 v137, v28, v137
	v_sub_f32_e32 v137, v137, v181
	v_add_f32_e32 v139, v29, v139
	v_sub_f32_e32 v139, v139, v181
	s_waitcnt lgkmcnt(0)
	v_add_f32_e32 v134, v10, v134
	v_sub_f32_e32 v134, v134, v181
	v_exp_f32_e32 v150, v134
	v_exp_f32_e32 v134, v135
	v_add_u32_e32 v135, s83, v171
	ds_read_b32 v135, v135 offset:8192
	v_add_f32_e32 v154, v30, v154
	v_sub_f32_e32 v154, v154, v181
	v_add_f32_e32 v199, v31, v199
	v_sub_f32_e32 v199, v199, v181
	s_waitcnt lgkmcnt(0)
	v_add_f32_e32 v135, v11, v135
	v_sub_f32_e32 v135, v135, v181
	v_exp_f32_e32 v151, v135
	v_exp_f32_e32 v135, v136
	v_add_u32_e32 v136, s83, v169
	ds_read_b32 v136, v136 offset:8192
	v_exp_f32_e32 v199, v199
	v_cndmask_b32_e64 v111, 0, v111, s[8:9]
	v_cndmask_b32_e64 v110, 0, v110, s[6:7]
	v_cndmask_b32_e64 v125, 0, v125, s[10:11]
	s_waitcnt lgkmcnt(0)
	v_add_f32_e32 v136, v12, v136
	v_sub_f32_e32 v136, v136, v181
	v_exp_f32_e32 v152, v136
	v_exp_f32_e32 v136, v137
	v_add_u32_e32 v137, s83, v167
	ds_read_b32 v137, v137 offset:8192
	v_cndmask_b32_e64 v124, 0, v124, s[12:13]
	v_cndmask_b32_e64 v129, 0, v129, s[14:15]
	v_cndmask_b32_e64 v128, 0, v128, s[16:17]
	v_cndmask_b32_e64 v131, 0, v131, s[18:19]
	s_waitcnt lgkmcnt(0)
	v_add_f32_e32 v137, v13, v137
	v_sub_f32_e32 v137, v137, v181
	v_exp_f32_e32 v153, v137
	v_exp_f32_e32 v137, v139
	v_add_u32_e32 v139, s83, v165
	ds_read_b32 v139, v139 offset:8192
	v_cndmask_b32_e64 v130, 0, v130, s[20:21]
	v_cndmask_b32_e64 v133, 0, v133, s[22:23]
	v_cndmask_b32_e64 v132, 0, v132, s[24:25]
	v_cndmask_b32_e64 v135, 0, v135, s[26:27]
	s_waitcnt lgkmcnt(0)
	v_add_f32_e32 v139, v14, v139
	v_sub_f32_e32 v139, v139, v181
	v_exp_f32_e32 v155, v139
	v_exp_f32_e32 v139, v154
	v_add_u32_e32 v154, s83, v163
	ds_read_b32 v154, v154 offset:8192
	v_cndmask_b32_e64 v134, 0, v134, s[28:29]
	v_cndmask_b32_e64 v137, 0, v137, s[30:31]
	v_cndmask_b32_e64 v136, 0, v136, s[34:35]
	v_cndmask_b32_e64 v139, 0, v139, s[36:37]
	s_waitcnt lgkmcnt(0)
	v_add_f32_e32 v154, v15, v154
	v_sub_f32_e32 v154, v154, v181
	v_exp_f32_e32 v200, v154
	v_pk_add_f32 v[110:111], v[126:127], v[110:111]
	v_pk_add_f32 v[124:125], v[122:123], v[124:125]
	v_pk_add_f32 v[128:129], v[120:121], v[128:129]
	v_pk_add_f32 v[130:131], v[118:119], v[130:131]
	v_pk_add_f32 v[132:133], v[116:117], v[132:133]
	v_pk_add_f32 v[134:135], v[114:115], v[134:135]
	v_pk_add_f32 v[136:137], v[112:113], v[136:137]
	v_add_f32_e32 v139, v198, v139
	v_cndmask_b32_e64 v140, 0, v140, s[68:69]
	v_cndmask_b32_e64 v141, 0, v141, s[70:71]
	v_cndmask_b32_e64 v142, 0, v142, s[50:51]
	v_cndmask_b32_e64 v143, 0, v143, s[48:49]
	v_cndmask_b32_e64 v144, 0, v144, s[46:47]
	v_cndmask_b32_e64 v145, 0, v145, s[44:45]
	v_cndmask_b32_e64 v146, 0, v146, s[42:43]
	v_cndmask_b32_e64 v147, 0, v147, s[40:41]
	v_cndmask_b32_e64 v148, 0, v148, s[66:67]
	v_cndmask_b32_e64 v149, 0, v149, s[64:65]
	v_cndmask_b32_e64 v150, 0, v150, s[62:63]
	v_cndmask_b32_e64 v151, 0, v151, s[60:61]
	v_cndmask_b32_e64 v152, 0, v152, s[58:59]
	v_cndmask_b32_e64 v153, 0, v153, s[56:57]
	v_cndmask_b32_e64 v154, 0, v155, s[54:55]
	v_cndmask_b32_e64 v155, 0, v200, s[52:53]
	v_cndmask_b32_e64 v199, 0, v199, s[38:39]
	s_mov_b64 s[2:3], 0
